# P2 state_copies: 10 per-thread float4 copies batched (all loads in flight, then stores) instead of load-wait-store per trip; on top of attn MODE0 loop trims
# speedup vs baseline: 1.0210x; 1.0064x over previous
; __device__ __forceinline__ void state_copies(const Prm& P, Ctx& C) {
;     const int gt = C.bid * NTHR + C.tid, NGT = C.G * NTHR;
;     for (int i = gt; i < DB * 508 * 64; i += NGT) { const int b = i / (508 * 64), r = i % (508 * 64); ((f32x4*)(P.out + O_WINS + (size_t)b * 512 * 256))[r] = ((const f32x4*)(P.state_win + ((size_t)b * 512 + 4) * 256))[r]; }
;     for (int i = gt; i < DB * 26 * 128; i += NGT) { const int b = i / (26 * 128), r = i % (26 * 128); ((f32x4*)(P.out + O_CONVS + (size_t)b * 30 * 512))[r] = ((const f32x4*)(P.state_conv + ((size_t)b * 30 + 4) * 512))[r]; }
;     for (int i = gt; i < DB * 11 * 256; i += NGT) { const int b = i / (11 * 256), r = i % (11 * 256); ((f32x4*)(P.out + O_POOLS + (size_t)b * 15 * 1024))[r] = ((const f32x4*)(P.state_pool + ((size_t)b * 15 + 4) * 1024))[r]; }
; }
.LBB0_997:
	v_readlane_b32 s0, v250, 8
	s_lshl_b32 s6, s0, 9
	v_lshl_add_u32 v0, s77, 9, v120
	s_cmpk_lg_i32 s0, 0x100
	s_cbranch_scc1 .Lsc_generic
	v_readlane_b32 s44, v250, 20
	v_readlane_b32 s45, v250, 21
	v_readlane_b32 s46, v250, 22
	v_readlane_b32 s47, v250, 23
	v_readlane_b32 s48, v250, 24
	v_readlane_b32 s49, v250, 25
	v_readlane_b32 s18, v250, 51
	v_readlane_b32 s19, v250, 52
	s_nop 3
	s_add_u32 s44, s44, 0x1000
	s_addc_u32 s45, s45, 0
	s_add_u32 s46, s46, 0x2000
	s_addc_u32 s47, s47, 0
	s_add_u32 s48, s48, 0x4000
	s_addc_u32 s49, s49, 0
	s_add_u32 s2, s18, 0xc338000
	s_addc_u32 s3, s19, 0
	s_add_u32 s4, s18, 0xd338000
	s_addc_u32 s5, s19, 0
	s_add_u32 s16, s18, 0xd518000
	s_addc_u32 s17, s19, 0
	s_mov_b32 s7, 0x81020409
	v_mov_b32_e32 v1, v0
	v_mul_hi_i32 v2, v1, s7
	v_add_u32_e32 v2, v2, v1
	v_lshrrev_b32_e32 v3, 31, v2
	v_ashrrev_i32_e32 v2, 14, v2
	v_add_u32_e32 v2, v2, v3
	v_mul_i32_i24_e32 v3, 0x7f00, v2
	v_sub_u32_e32 v3, v1, v3
	v_lshlrev_b32_e32 v2, 19, v2
	v_lshl_add_u32 v4, v3, 4, v2
	global_load_dwordx4 v[16:19], v4, s[44:45]
	v_add_u32_e32 v1, 0x20000, v0
	v_mul_hi_i32 v2, v1, s7
	v_add_u32_e32 v2, v2, v1
	v_lshrrev_b32_e32 v3, 31, v2
	v_ashrrev_i32_e32 v2, 14, v2
	v_add_u32_e32 v2, v2, v3
	v_mul_i32_i24_e32 v3, 0x7f00, v2
	v_sub_u32_e32 v3, v1, v3
	v_lshlrev_b32_e32 v2, 19, v2
	v_lshl_add_u32 v5, v3, 4, v2
	global_load_dwordx4 v[20:23], v5, s[44:45]
	v_add_u32_e32 v1, 0x40000, v0
	v_mul_hi_i32 v2, v1, s7
	v_add_u32_e32 v2, v2, v1
	v_lshrrev_b32_e32 v3, 31, v2
	v_ashrrev_i32_e32 v2, 14, v2
	v_add_u32_e32 v2, v2, v3
	v_mul_i32_i24_e32 v3, 0x7f00, v2
	v_sub_u32_e32 v3, v1, v3
	v_lshlrev_b32_e32 v2, 19, v2
	v_lshl_add_u32 v6, v3, 4, v2
	global_load_dwordx4 v[24:27], v6, s[44:45]
	v_add_u32_e32 v1, 0x60000, v0
	v_mul_hi_i32 v2, v1, s7
	v_add_u32_e32 v2, v2, v1
	v_lshrrev_b32_e32 v3, 31, v2
	v_ashrrev_i32_e32 v2, 14, v2
	v_add_u32_e32 v2, v2, v3
	v_mul_i32_i24_e32 v3, 0x7f00, v2
	v_sub_u32_e32 v3, v1, v3
	v_lshlrev_b32_e32 v2, 19, v2
	v_lshl_add_u32 v7, v3, 4, v2
	global_load_dwordx4 v[28:31], v7, s[44:45]
	v_add_u32_e32 v1, 0x80000, v0
	v_mul_hi_i32 v2, v1, s7
	v_add_u32_e32 v2, v2, v1
	v_lshrrev_b32_e32 v3, 31, v2
	v_ashrrev_i32_e32 v2, 14, v2
	v_add_u32_e32 v2, v2, v3
	v_mul_i32_i24_e32 v3, 0x7f00, v2
	v_sub_u32_e32 v3, v1, v3
	v_lshlrev_b32_e32 v2, 19, v2
	v_lshl_add_u32 v8, v3, 4, v2
	global_load_dwordx4 v[32:35], v8, s[44:45]
	v_add_u32_e32 v1, 0xa0000, v0
	v_mul_hi_i32 v2, v1, s7
	v_add_u32_e32 v2, v2, v1
	v_lshrrev_b32_e32 v3, 31, v2
	v_ashrrev_i32_e32 v2, 14, v2
	v_add_u32_e32 v2, v2, v3
	v_mul_i32_i24_e32 v3, 0x7f00, v2
	v_sub_u32_e32 v3, v1, v3
	v_lshlrev_b32_e32 v2, 19, v2
	v_lshl_add_u32 v9, v3, 4, v2
	global_load_dwordx4 v[36:39], v9, s[44:45]
	v_add_u32_e32 v1, 0xc0000, v0
	v_mul_hi_i32 v2, v1, s7
	v_add_u32_e32 v2, v2, v1
	v_lshrrev_b32_e32 v3, 31, v2
	v_ashrrev_i32_e32 v2, 14, v2
	v_add_u32_e32 v2, v2, v3
	v_mul_i32_i24_e32 v3, 0x7f00, v2
	v_sub_u32_e32 v3, v1, v3
	v_lshlrev_b32_e32 v2, 19, v2
	v_lshl_add_u32 v10, v3, 4, v2
	global_load_dwordx4 v[40:43], v10, s[44:45]
	v_add_u32_e32 v1, 0xe0000, v0
	v_min_u32_e32 v1, 0xfdfff, v1
	v_mul_hi_i32 v2, v1, s7
	v_add_u32_e32 v2, v2, v1
	v_lshrrev_b32_e32 v3, 31, v2
	v_ashrrev_i32_e32 v2, 14, v2
	v_add_u32_e32 v2, v2, v3
	v_mul_i32_i24_e32 v3, 0x7f00, v2
	v_sub_u32_e32 v3, v1, v3
	v_lshlrev_b32_e32 v2, 19, v2
	v_lshl_add_u32 v11, v3, 4, v2
	global_load_dwordx4 v[44:47], v11, s[44:45]
	s_mov_b32 s7, 0x4ec4ec4f
	v_min_u32_e32 v1, 0x19fff, v0
	v_mul_hi_i32 v2, v1, s7
	v_lshrrev_b32_e32 v3, 31, v2
	v_ashrrev_i32_e32 v2, 10, v2
	v_add_u32_e32 v2, v2, v3
	v_mul_i32_i24_e32 v3, 0xd00, v2
	v_mul_i32_i24_e32 v2, 30, v2
	v_sub_u32_e32 v3, v1, v3
	v_lshlrev_b32_e32 v2, 11, v2
	v_lshl_add_u32 v12, v3, 4, v2
	global_load_dwordx4 v[48:51], v12, s[46:47]
	s_mov_b32 s7, 0x2e8ba2e9
	v_min_u32_e32 v1, 0x15fff, v0
	v_mul_hi_i32 v2, v1, s7
	v_lshrrev_b32_e32 v3, 31, v2
	v_ashrrev_i32_e32 v2, 9, v2
	v_add_u32_e32 v2, v2, v3
	v_mul_i32_i24_e32 v3, 0xb00, v2
	v_mul_i32_i24_e32 v2, 15, v2
	v_sub_u32_e32 v3, v1, v3
	v_lshlrev_b32_e32 v2, 12, v2
	v_lshl_add_u32 v13, v3, 4, v2
	global_load_dwordx4 v[52:55], v13, s[48:49]
	s_waitcnt vmcnt(9)
	global_store_dwordx4 v4, v[16:19], s[2:3]
	s_waitcnt vmcnt(9)
	global_store_dwordx4 v5, v[20:23], s[2:3]
	s_waitcnt vmcnt(9)
	global_store_dwordx4 v6, v[24:27], s[2:3]
	s_waitcnt vmcnt(9)
	global_store_dwordx4 v7, v[28:31], s[2:3]
	s_waitcnt vmcnt(9)
	global_store_dwordx4 v8, v[32:35], s[2:3]
	s_waitcnt vmcnt(9)
	global_store_dwordx4 v9, v[36:39], s[2:3]
	s_waitcnt vmcnt(9)
	global_store_dwordx4 v10, v[40:43], s[2:3]
	s_waitcnt vmcnt(9)
	v_cmp_gt_u32_e32 vcc, 0x1e000, v0
	s_and_saveexec_b64 s[20:21], vcc
	global_store_dwordx4 v11, v[44:47], s[2:3]
	s_mov_b64 exec, s[20:21]
	s_waitcnt vmcnt(7)
	v_cmp_gt_u32_e32 vcc, 0x1a000, v0
	s_and_saveexec_b64 s[20:21], vcc
	global_store_dwordx4 v12, v[48:51], s[4:5]
	s_mov_b64 exec, s[20:21]
	v_cmp_gt_u32_e32 vcc, 0x16000, v0
	s_and_saveexec_b64 s[20:21], vcc
	global_store_dwordx4 v13, v[52:55], s[16:17]
	s_mov_b64 exec, s[20:21]
	s_branch .LBB0_1006
.Lsc_generic:
	s_mov_b32 s0, 0xfe000
	v_cmp_gt_i32_e32 vcc, s0, v0
	s_and_saveexec_b64 s[0:1], vcc
	v_readlane_b32 s36, v250, 12
	v_readlane_b32 s44, v250, 20
	v_readlane_b32 s45, v250, 21
	v_readlane_b32 s37, v250, 13
	v_readlane_b32 s38, v250, 14
	v_readlane_b32 s39, v250, 15
	v_readlane_b32 s40, v250, 16
	v_readlane_b32 s41, v250, 17
	v_readlane_b32 s42, v250, 18
	v_readlane_b32 s43, v250, 19
	v_readlane_b32 s46, v250, 22
	v_readlane_b32 s47, v250, 23
	v_readlane_b32 s48, v250, 24
	v_readlane_b32 s49, v250, 25
	v_readlane_b32 s50, v250, 26
	v_readlane_b32 s51, v250, 27
	s_cbranch_execz .LBB0_1000
	v_readlane_b32 s16, v250, 49
	v_readlane_b32 s18, v250, 51
	v_readlane_b32 s19, v250, 52
	s_add_u32 s2, s18, 0xc338000
	s_addc_u32 s3, s19, 0
	s_mov_b64 s[4:5], 0
	s_mov_b32 s7, 0x81020409
	s_mov_b32 s8, 0xfdfff
	v_mov_b32_e32 v1, v0
	v_readlane_b32 s17, v250, 50
	v_readlane_b32 s20, v250, 53
	v_readlane_b32 s21, v250, 54
	v_readlane_b32 s22, v250, 55
	v_readlane_b32 s23, v250, 56
